# GATES GEMM unit order row-major (4 rows x 8 cols per XCD round) via coordinate swap in all eight index-math copies (run 1)
# baseline (speedup 1.0000x reference)
;     __device__ bool next(int i, Unit& u) const { if (r0 + i >= r1) return false; return base.next(r0 + i, u); }
;     __device__ bool next(int i, Unit& u) const { const int L = i * G + c; if (L >= 256) return false; u.pm = L; u.pn = L >> 3; return true; }
;     __device__ bool next(int i, Unit& u) const {
;         const long L = (long)i * G + c; if (L >= nwg) return false;
;         int wgid = (int)L; { const int q = nwg / NXCD, r = nwg % NXCD, xcd = wgid % NXCD, off = wgid / NXCD; wgid = (xcd < r ? xcd * (q + 1) : r * (q + 1) + (xcd - r) * q) + off; }
;         const int nig = WGM * nN, gid = wgid / nig, fm = gid * WGM, gsz = (nM - fm) < WGM ? (nM - fm) : WGM;
;         u.pm = fm + ((wgid % nig) % gsz); u.pn = (wgid % nig) / gsz; return true;
; template <class Epi, class Sched>
; __device__ __forceinline__ void gemm_phase(LAS unsigned char* lds, const Gemm g, const Sched& S, const Epi& E, int wave_id) {
;     ...
;     for (int i = 0; i < 2; ++i) { int R, C; stage_rc(tid * 16 + i * 8192, R, C); const int Rb = (R & ~31) + perm32(R & 31);
;         voffA[i] = (unsigned)(R * g.lda + C) * 2u; voffB[i] = (unsigned)(Rb * g.ldb + C) * 2u; }
;     const size_t kstep = (size_t)(BK * 2);
;     const size_t hstepA = (size_t)HALF * g.lda * 2, hstepB = (size_t)HALF * g.ldb * 2;
;     const size_t tstepA = 2 * hstepA, tstepB = 2 * hstepB;
;     const unsigned ldsw = (unsigned)wid * 1024u;
;     const int aoff = lds_byte(wr * 64 + fr, fq * 8), boff = lds_byte(wc * 32 + fr, fq * 8);
;     ...
;     Unit cur, nxt; int ui = 0;
;     if (!S.next(0, cur)) return;
;     f32x4 acc[2][2][4][2];
; #pragma unroll
;     for (int a = 0; a < 2; ++a)
; #pragma unroll
;         for (int b = 0; b < 2; ++b)
; #pragma unroll
;             for (int m = 0; m < 4; ++m)
; #pragma unroll
;                 for (int n = 0; n < 2; ++n) acc[a][b][m][n] = (f32x4){0.f, 0.f, 0.f, 0.f};
;     bf16x8 At[4][2], B0[2][2], B1[2][2];
;     const char* cA = (const char*)g.A + (size_t)cur.pm * tstepA; const char* cB = (const char*)g.Bt + (size_t)cur.pn * tstepB;
;     PG8_STAGE(PG8_SB(0, 0), cB, voffB); PG8_STAGE(PG8_SB(0, 1), cB + hstepB, voffB); PG8_STAGE(PG8_SA(0, 0), cA, voffA); PG8_STAGE(PG8_SA(0, 1), cA + hstepA, voffA);
.LBB0_660:
	v_ashrrev_i32_e32 v1, 31, v8
	v_lshrrev_b32_e32 v1, 26, v1
	v_add_u32_e32 v1, v8, v1
	v_ashrrev_i32_e32 v9, 6, v1
	v_bfe_i32 v1, v8, 27, 1
	v_lshlrev_b32_e32 v0, 4, v8
	v_lshrrev_b32_e32 v1, 22, v1
	v_add_u32_e32 v1, v0, v1
	v_and_b32_e32 v1, 0xfffffc00, v1
	v_sub_u32_e32 v1, v0, v1
	v_lshrrev_b32_e32 v2, 4, v1
	v_bitop3_b32 v1, v2, v1, 32 bitop3:0x6c
	v_ashrrev_i32_e32 v3, 31, v1
	v_lshrrev_b32_e32 v3, 26, v3
	v_add_u32_e32 v3, v1, v3
	v_lshlrev_b32_e32 v2, 3, v9
	v_ashrrev_i32_e32 v10, 6, v3
	v_and_b32_e32 v3, 0xc0, v3
	v_and_b32_e32 v2, -16, v2
	v_sub_u32_e32 v1, v1, v3
	v_mov_b32_e32 v3, 1
	v_add_u32_e32 v2, v10, v2
	v_ashrrev_i16_sdwa v1, v3, sext(v1) dst_sel:DWORD dst_unused:UNUSED_PAD src0_sel:DWORD src1_sel:BYTE_0
	v_lshlrev_b32_e32 v4, 5, v9
	v_bfe_i32 v11, v1, 0, 16
	v_lshlrev_b32_e32 v1, 1, v2
	v_lshrrev_b32_e32 v5, 2, v2
	v_and_b32_e32 v6, 3, v10
	s_mov_b32 s5, 0x1fffe0
	v_and_b32_e32 v4, 32, v4
	v_and_b32_e32 v1, 24, v1
	v_and_b32_e32 v5, 4, v5
	v_and_or_b32 v6, v2, s5, v6
	v_or3_b32 v1, v6, v5, v1
	v_add_lshl_u32 v4, v4, v11, 1
	v_add_u32_e32 v0, 0x2000, v0
	v_lshl_add_u32 v130, v1, 11, v4
	v_ashrrev_i32_e32 v1, 31, v0
	v_lshrrev_b32_e32 v1, 22, v1
	v_add_u32_e32 v1, v0, v1
	v_ashrrev_i32_e32 v12, 10, v1
	v_mul_i32_i24_e32 v1, 0x400, v12
	v_sub_u32_e32 v0, v0, v1
	v_lshrrev_b32_e32 v1, 4, v0
	v_bitop3_b32 v0, v1, v0, 32 bitop3:0x6c
	v_lshl_add_u32 v128, v2, 11, v4
	v_ashrrev_i32_e32 v2, 31, v0
	s_ashr_i32 s4, s7, 3
	v_lshrrev_b32_e32 v2, 26, v2
	s_add_u32 s15, s92, 0x3400000
	v_add_u32_e32 v2, v0, v2
	s_addc_u32 s33, s93, 0
	v_lshlrev_b32_e32 v1, 3, v12
	v_ashrrev_i32_e32 v13, 6, v2
	v_and_b32_e32 v2, 0xc0, v2
	s_add_u32 s44, s92, 0xa00000
	v_and_b32_e32 v1, -16, v1
	v_sub_u32_e32 v0, v0, v2
	s_addc_u32 s45, s93, 0
	v_add_u32_e32 v1, v13, v1
	v_ashrrev_i16_sdwa v0, v3, sext(v0) dst_sel:DWORD dst_unused:UNUSED_PAD src0_sel:DWORD src1_sel:BYTE_0
	v_and_b32_e32 v3, 3, v13
	s_add_i32 s4, s6, s4
	v_and_or_b32 v3, v1, s5, v3
	s_ashr_i32 s5, s4, 31
	s_lshr_b32 s5, s5, 26
	s_add_i32 s5, s4, s5
	s_ashr_i32 s6, s5, 6
	s_and_b32 s5, s5, 0xffc0
	s_sub_i32 s4, s4, s5
	s_bfe_i32 s5, s4, 0x80000
	s_bfe_u32 s5, s5, 0x3000c
	s_add_i32 s5, s4, s5
	s_and_b32 s7, s5, 0xf8
	s_sub_i32 s4, s4, s7
	s_lshl_b32 s6, s6, 3
	s_sext_i32_i8 s4, s4
	s_add_i32 s30, s6, s4
	s_bfe_i32 s4, s5, 0x80000
	s_sext_i32_i16 s4, s4
	s_lshr_b32 s9, s80, 8
	s_lshr_b32 s8, s4, 3
	s_and_b32 s4, s30, 7
	s_andn2_b32 s30, s30, 7
	s_add_i32 s30, s30, s8
	s_mov_b32 s8, s4
	s_ashr_i32 s31, s30, 31
	s_bfe_i64 s[6:7], s[8:9], 0x100000
	s_lshl_b32 s46, s97, 10
	s_lshl_b64 s[4:5], s[30:31], 19
	s_lshl_b64 s[6:7], s[6:7], 19
	s_add_u32 s36, s44, s6
	v_lshlrev_b32_e32 v4, 5, v12
	v_bfe_i32 v14, v0, 0, 16
	v_lshlrev_b32_e32 v0, 1, v1
	v_lshrrev_b32_e32 v2, 2, v1
	s_addc_u32 s37, s45, s7
	s_add_i32 s31, s46, 0
	v_and_b32_e32 v4, 32, v4
	v_and_b32_e32 v0, 24, v0
	v_and_b32_e32 v2, 4, v2
	s_add_i32 m0, s31, 0x10000
	v_or3_b32 v0, v3, v2, v0
	v_add_lshl_u32 v2, v4, v14, 1
	global_load_lds_dwordx4 v130, s[36:37]
	s_add_i32 m0, s31, 0x12000
	v_lshl_add_u32 v134, v0, 11, v2
	s_add_u32 s6, s36, 0x40000
	global_load_lds_dwordx4 v134, s[36:37]
	s_addc_u32 s7, s37, 0
	s_add_i32 m0, s31, 0x14000
	v_lshl_add_u32 v132, v1, 11, v2
	global_load_lds_dwordx4 v130, s[6:7]
	s_add_i32 m0, s31, 0x16000
	s_add_u32 s34, s15, s4
	s_addc_u32 s35, s33, s5
	s_add_i32 s47, s31, 0x2000
	global_load_lds_dwordx4 v134, s[6:7]
	s_mov_b32 m0, s31
	s_add_u32 s4, s34, 0x40000
	global_load_lds_dwordx4 v128, s[34:35]
	s_mov_b32 m0, s47
	s_addc_u32 s5, s35, 0
	s_add_i32 s48, s31, 0x4000
	global_load_lds_dwordx4 v132, s[34:35]
	s_mov_b32 m0, s48
	s_add_i32 s49, s31, 0x6000
	global_load_lds_dwordx4 v128, s[4:5]
	s_mov_b32 m0, s49
	v_mov_b32_e32 v131, 0
	global_load_lds_dwordx4 v132, s[4:5]
	v_mov_b32_e32 v135, v131
	v_mov_b32_e32 v129, v131
	v_mov_b32_e32 v133, v131
	s_cmp_eq_u32 s9, 1
	s_mov_b32 s50, 0
	v_lshl_add_u64 v[6:7], s[36:37], 0, v[130:131]
	v_lshl_add_u64 v[4:5], s[36:37], 0, v[134:135]
	v_lshl_add_u64 v[0:1], s[34:35], 0, v[128:129]
	s_cselect_b64 s[4:5], -1, 0
	s_cmp_lg_u32 s9, 1
	v_lshl_add_u64 v[2:3], s[34:35], 0, v[132:133]
	s_cbranch_scc1 .LBB0_662
	s_barrier

;     __device__ bool next(int i, Unit& u) const { if (r0 + i >= r1) return false; return base.next(r0 + i, u); }
;     __device__ bool next(int i, Unit& u) const { const int L = i * G + c; if (L >= 256) return false; u.pm = L; u.pn = L >> 3; return true; }
;     __device__ bool next(int i, Unit& u) const {
;         const long L = (long)i * G + c; if (L >= nwg) return false;
;         int wgid = (int)L; { const int q = nwg / NXCD, r = nwg % NXCD, xcd = wgid % NXCD, off = wgid / NXCD; wgid = (xcd < r ? xcd * (q + 1) : r * (q + 1) + (xcd - r) * q) + off; }
;         const int nig = WGM * nN, gid = wgid / nig, fm = gid * WGM, gsz = (nM - fm) < WGM ? (nM - fm) : WGM;
;         u.pm = fm + ((wgid % nig) % gsz); u.pn = (wgid % nig) / gsz; return true;
.LBB0_671:
	s_ashr_i32 s16, s22, 3
	s_add_i32 s16, s24, s16
	s_ashr_i32 s17, s16, 31
	s_lshr_b32 s17, s17, 26
	s_add_i32 s17, s16, s17
	s_ashr_i32 s22, s17, 6
	s_lshl_b32 s22, s22, 3
	s_sub_i32 s23, 0x80, s22
	s_min_i32 s23, s23, 8
	s_abs_i32 s24, s23
	v_cvt_f32_u32_e32 v0, s24
	s_sub_i32 s26, 0, s24
	s_andn2_b32 s17, s17, 63
	s_sub_i32 s17, s16, s17
	v_rcp_iflag_f32_e32 v0, v0
	s_abs_i32 s16, s17
	s_xor_b32 s25, s17, s23
	s_ashr_i32 s25, s25, 31
	v_mul_f32_e32 v0, 0x4f7ffffe, v0
	v_cvt_u32_f32_e32 v0, v0
	s_nop 0
	v_readfirstlane_b32 s27, v0
	s_mul_i32 s26, s26, s27
	s_mul_hi_u32 s26, s27, s26
	s_add_i32 s27, s27, s26
	s_mul_hi_u32 s26, s16, s27
	s_mul_i32 s27, s26, s24
	s_sub_i32 s16, s16, s27
	s_add_i32 s28, s26, 1
	s_sub_i32 s27, s16, s24
	s_cmp_ge_u32 s16, s24
	s_cselect_b32 s26, s28, s26
	s_cselect_b32 s16, s27, s16
	s_add_i32 s27, s26, 1
	s_cmp_ge_u32 s16, s24
	s_cselect_b32 s16, s27, s26
	s_xor_b32 s16, s16, s25
	s_sub_i32 s16, s16, s25
	s_mul_i32 s23, s16, s23
	s_sub_i32 s17, s17, s23
	s_add_i32 s22, s22, s17
	s_and_b32 s17, s22, 7
	s_andn2_b32 s22, s22, 7
	s_add_i32 s22, s22, s16
	s_mov_b32 s16, s17
	s_mov_b64 s[24:25], -1

;     __device__ bool next(int i, Unit& u) const { if (r0 + i >= r1) return false; return base.next(r0 + i, u); }
;     __device__ bool next(int i, Unit& u) const { const int L = i * G + c; if (L >= 256) return false; u.pm = L; u.pn = L >> 3; return true; }
;     __device__ bool next(int i, Unit& u) const {
;         const long L = (long)i * G + c; if (L >= nwg) return false;
;         int wgid = (int)L; { const int q = nwg / NXCD, r = nwg % NXCD, xcd = wgid % NXCD, off = wgid / NXCD; wgid = (xcd < r ? xcd * (q + 1) : r * (q + 1) + (xcd - r) * q) + off; }
;         const int nig = WGM * nN, gid = wgid / nig, fm = gid * WGM, gsz = (nM - fm) < WGM ? (nM - fm) : WGM;
;         u.pm = fm + ((wgid % nig) % gsz); u.pn = (wgid % nig) / gsz; return true;
; template <class Epi, class Sched>
; __device__ __forceinline__ void gemm_phase(LAS unsigned char* lds, const Gemm g, const Sched& S, const Epi& E, int wave_id) {
;     ...
;     for (int i = 0; i < 2; ++i) { int R, C; stage_rc(tid * 16 + i * 8192, R, C); const int Rb = (R & ~31) + perm32(R & 31);
;         voffA[i] = (unsigned)(R * g.lda + C) * 2u; voffB[i] = (unsigned)(Rb * g.ldb + C) * 2u; }
;     const size_t kstep = (size_t)(BK * 2);
;     const size_t hstepA = (size_t)HALF * g.lda * 2, hstepB = (size_t)HALF * g.ldb * 2;
;     const size_t tstepA = 2 * hstepA, tstepB = 2 * hstepB;
;     const unsigned ldsw = (unsigned)wid * 1024u;
;     const int aoff = lds_byte(wr * 64 + fr, fq * 8), boff = lds_byte(wc * 32 + fr, fq * 8);
;     ...
;     Unit cur, nxt; int ui = 0;
;     if (!S.next(0, cur)) return;
;     f32x4 acc[2][2][4][2];
; #pragma unroll
;     for (int a = 0; a < 2; ++a)
; #pragma unroll
;         for (int b = 0; b < 2; ++b)
; #pragma unroll
;             for (int m = 0; m < 4; ++m)
; #pragma unroll
;                 for (int n = 0; n < 2; ++n) acc[a][b][m][n] = (f32x4){0.f, 0.f, 0.f, 0.f};
;     bf16x8 At[4][2], B0[2][2], B1[2][2];
;     const char* cA = (const char*)g.A + (size_t)cur.pm * tstepA; const char* cB = (const char*)g.Bt + (size_t)cur.pn * tstepB;
;     PG8_STAGE(PG8_SB(0, 0), cB, voffB); PG8_STAGE(PG8_SB(0, 1), cB + hstepB, voffB); PG8_STAGE(PG8_SA(0, 0), cA, voffA); PG8_STAGE(PG8_SA(0, 1), cA + hstepA, voffA);
.LBB0_715:
	v_ashrrev_i32_e32 v1, 31, v8
	v_lshrrev_b32_e32 v1, 26, v1
	v_add_u32_e32 v1, v8, v1
	v_ashrrev_i32_e32 v9, 6, v1
	v_bfe_i32 v1, v8, 27, 1
	v_lshlrev_b32_e32 v0, 4, v8
	v_lshrrev_b32_e32 v1, 22, v1
	v_add_u32_e32 v1, v0, v1
	v_and_b32_e32 v1, 0xfffffc00, v1
	v_sub_u32_e32 v1, v0, v1
	v_lshrrev_b32_e32 v2, 4, v1
	v_bitop3_b32 v1, v2, v1, 32 bitop3:0x6c
	v_ashrrev_i32_e32 v3, 31, v1
	v_lshrrev_b32_e32 v3, 26, v3
	v_add_u32_e32 v3, v1, v3
	v_lshlrev_b32_e32 v2, 3, v9
	v_ashrrev_i32_e32 v10, 6, v3
	v_and_b32_e32 v3, 0xc0, v3
	v_and_b32_e32 v2, -16, v2
	v_sub_u32_e32 v1, v1, v3
	v_mov_b32_e32 v3, 1
	v_add_u32_e32 v2, v10, v2
	v_ashrrev_i16_sdwa v1, v3, sext(v1) dst_sel:DWORD dst_unused:UNUSED_PAD src0_sel:DWORD src1_sel:BYTE_0
	v_lshlrev_b32_e32 v4, 5, v9
	v_bfe_i32 v11, v1, 0, 16
	v_lshlrev_b32_e32 v1, 1, v2
	v_lshrrev_b32_e32 v5, 2, v2
	v_and_b32_e32 v6, 3, v10
	s_mov_b32 s5, 0x1fffe0
	v_and_b32_e32 v4, 32, v4
	v_and_b32_e32 v1, 24, v1
	v_and_b32_e32 v5, 4, v5
	v_and_or_b32 v6, v2, s5, v6
	v_or3_b32 v1, v6, v5, v1
	v_add_lshl_u32 v4, v4, v11, 1
	v_add_u32_e32 v0, 0x2000, v0
	v_lshl_add_u32 v130, v1, 11, v4
	v_ashrrev_i32_e32 v1, 31, v0
	v_lshrrev_b32_e32 v1, 22, v1
	v_add_u32_e32 v1, v0, v1
	v_ashrrev_i32_e32 v12, 10, v1
	v_mul_i32_i24_e32 v1, 0x400, v12
	v_sub_u32_e32 v0, v0, v1
	v_lshrrev_b32_e32 v1, 4, v0
	v_bitop3_b32 v0, v1, v0, 32 bitop3:0x6c
	v_lshl_add_u32 v128, v2, 11, v4
	v_ashrrev_i32_e32 v2, 31, v0
	s_ashr_i32 s4, s7, 3
	v_lshrrev_b32_e32 v2, 26, v2
	s_add_u32 s15, s92, 0x3400000
	v_add_u32_e32 v2, v0, v2
	s_addc_u32 s33, s93, 0
	v_lshlrev_b32_e32 v1, 3, v12
	v_ashrrev_i32_e32 v13, 6, v2
	v_and_b32_e32 v2, 0xc0, v2
	s_add_u32 s38, s92, 0xa00000
	v_and_b32_e32 v1, -16, v1
	v_sub_u32_e32 v0, v0, v2
	s_addc_u32 s39, s93, 0
	v_add_u32_e32 v1, v13, v1
	v_ashrrev_i16_sdwa v0, v3, sext(v0) dst_sel:DWORD dst_unused:UNUSED_PAD src0_sel:DWORD src1_sel:BYTE_0
	v_and_b32_e32 v3, 3, v13
	s_add_i32 s4, s6, s4
	v_and_or_b32 v3, v1, s5, v3
	s_ashr_i32 s5, s4, 31
	s_lshr_b32 s5, s5, 26
	s_add_i32 s5, s4, s5
	s_ashr_i32 s6, s5, 6
	s_and_b32 s5, s5, 0xffc0
	s_sub_i32 s4, s4, s5
	s_bfe_i32 s5, s4, 0x80000
	s_bfe_u32 s5, s5, 0x3000c
	s_add_i32 s5, s4, s5
	s_and_b32 s7, s5, 0xf8
	s_sub_i32 s4, s4, s7
	s_lshl_b32 s6, s6, 3
	s_sext_i32_i8 s4, s4
	s_add_i32 s28, s6, s4
	s_bfe_i32 s4, s5, 0x80000
	s_sext_i32_i16 s4, s4
	s_lshr_b32 s8, s4, 3
	s_and_b32 s4, s28, 7
	s_andn2_b32 s28, s28, 7
	s_add_i32 s28, s28, s8
	s_mov_b32 s8, s4
	s_ashr_i32 s29, s28, 31
	s_bfe_i64 s[6:7], s[8:9], 0x100000
	s_lshl_b64 s[4:5], s[28:29], 19
	s_lshl_b64 s[6:7], s[6:7], 19
	s_add_u32 s34, s38, s6
	v_lshlrev_b32_e32 v4, 5, v12
	v_bfe_i32 v14, v0, 0, 16
	v_lshlrev_b32_e32 v0, 1, v1
	v_lshrrev_b32_e32 v2, 2, v1
	s_addc_u32 s35, s39, s7
	s_add_i32 s29, s44, 0
	v_and_b32_e32 v4, 32, v4
	v_and_b32_e32 v0, 24, v0
	v_and_b32_e32 v2, 4, v2
	s_add_i32 m0, s29, 0x10000
	v_or3_b32 v0, v3, v2, v0
	v_add_lshl_u32 v2, v4, v14, 1
	global_load_lds_dwordx4 v130, s[34:35]
	s_add_i32 m0, s29, 0x12000
	v_lshl_add_u32 v134, v0, 11, v2
	s_add_u32 s6, s34, 0x40000
	global_load_lds_dwordx4 v134, s[34:35]
	s_addc_u32 s7, s35, 0
	s_add_i32 m0, s29, 0x14000
	v_lshl_add_u32 v132, v1, 11, v2
	global_load_lds_dwordx4 v130, s[6:7]
	s_add_i32 m0, s29, 0x16000
	s_add_u32 s30, s15, s4
	s_addc_u32 s31, s33, s5
	s_add_i32 s45, s29, 0x2000
	global_load_lds_dwordx4 v134, s[6:7]
	s_mov_b32 m0, s29
	s_add_u32 s4, s30, 0x40000
	global_load_lds_dwordx4 v128, s[30:31]
	s_mov_b32 m0, s45
	s_addc_u32 s5, s31, 0
	s_add_i32 s46, s29, 0x4000
	global_load_lds_dwordx4 v132, s[30:31]
	s_mov_b32 m0, s46
	s_add_i32 s47, s29, 0x6000
	global_load_lds_dwordx4 v128, s[4:5]
	s_mov_b32 m0, s47
	v_mov_b32_e32 v131, 0
	global_load_lds_dwordx4 v132, s[4:5]
	v_mov_b32_e32 v135, v131
	v_mov_b32_e32 v129, v131
	v_mov_b32_e32 v133, v131
	s_cmp_eq_u32 s49, 1
	s_mov_b32 s48, 0
	v_lshl_add_u64 v[6:7], s[34:35], 0, v[130:131]
	v_lshl_add_u64 v[4:5], s[34:35], 0, v[134:135]
	v_lshl_add_u64 v[0:1], s[30:31], 0, v[128:129]
	s_cselect_b64 s[4:5], -1, 0
	s_cmp_lg_u32 s49, 1
	v_lshl_add_u64 v[2:3], s[30:31], 0, v[132:133]
	s_cbranch_scc1 .LBB0_717
	s_barrier

;     __device__ bool next(int i, Unit& u) const { if (r0 + i >= r1) return false; return base.next(r0 + i, u); }
;     __device__ bool next(int i, Unit& u) const { const int L = i * G + c; if (L >= 256) return false; u.pm = L; u.pn = L >> 3; return true; }
;     __device__ bool next(int i, Unit& u) const {
;         const long L = (long)i * G + c; if (L >= nwg) return false;
;         int wgid = (int)L; { const int q = nwg / NXCD, r = nwg % NXCD, xcd = wgid % NXCD, off = wgid / NXCD; wgid = (xcd < r ? xcd * (q + 1) : r * (q + 1) + (xcd - r) * q) + off; }
;         const int nig = WGM * nN, gid = wgid / nig, fm = gid * WGM, gsz = (nM - fm) < WGM ? (nM - fm) : WGM;
;         u.pm = fm + ((wgid % nig) % gsz); u.pn = (wgid % nig) / gsz; return true;
.LBB0_726:
	s_ashr_i32 s16, s20, 3
	s_add_i32 s16, s22, s16
	s_ashr_i32 s17, s16, 31
	s_lshr_b32 s17, s17, 26
	s_add_i32 s17, s16, s17
	s_ashr_i32 s20, s17, 6
	s_lshl_b32 s20, s20, 3
	s_sub_i32 s21, 0x80, s20
	s_min_i32 s21, s21, 8
	s_abs_i32 s22, s21
	v_cvt_f32_u32_e32 v0, s22
	s_sub_i32 s24, 0, s22
	s_andn2_b32 s17, s17, 63
	s_sub_i32 s17, s16, s17
	v_rcp_iflag_f32_e32 v0, v0
	s_abs_i32 s16, s17
	s_xor_b32 s23, s17, s21
	s_ashr_i32 s23, s23, 31
	v_mul_f32_e32 v0, 0x4f7ffffe, v0
	v_cvt_u32_f32_e32 v0, v0
	s_nop 0
	v_readfirstlane_b32 s25, v0
	s_mul_i32 s24, s24, s25
	s_mul_hi_u32 s24, s25, s24
	s_add_i32 s25, s25, s24
	s_mul_hi_u32 s24, s16, s25
	s_mul_i32 s25, s24, s22
	s_sub_i32 s16, s16, s25
	s_add_i32 s26, s24, 1
	s_sub_i32 s25, s16, s22
	s_cmp_ge_u32 s16, s22
	s_cselect_b32 s24, s26, s24
	s_cselect_b32 s16, s25, s16
	s_add_i32 s25, s24, 1
	s_cmp_ge_u32 s16, s22
	s_cselect_b32 s16, s25, s24
	s_xor_b32 s16, s16, s23
	s_sub_i32 s16, s16, s23
	s_mul_i32 s21, s16, s21
	s_sub_i32 s17, s17, s21
	s_add_i32 s20, s20, s17
	s_and_b32 s17, s20, 7
	s_andn2_b32 s20, s20, 7
	s_add_i32 s20, s20, s16
	s_mov_b32 s16, s17
	s_mov_b64 s[22:23], -1

;     __device__ bool next(int i, Unit& u) const { if (r0 + i >= r1) return false; return base.next(r0 + i, u); }
;     __device__ bool next(int i, Unit& u) const { const int L = i * G + c; if (L >= 256) return false; u.pm = L; u.pn = L >> 3; return true; }
;     __device__ bool next(int i, Unit& u) const {
;         const long L = (long)i * G + c; if (L >= nwg) return false;
;         int wgid = (int)L; { const int q = nwg / NXCD, r = nwg % NXCD, xcd = wgid % NXCD, off = wgid / NXCD; wgid = (xcd < r ? xcd * (q + 1) : r * (q + 1) + (xcd - r) * q) + off; }
;         const int nig = WGM * nN, gid = wgid / nig, fm = gid * WGM, gsz = (nM - fm) < WGM ? (nM - fm) : WGM;
;         u.pm = fm + ((wgid % nig) % gsz); u.pn = (wgid % nig) / gsz; return true;
; template <class Epi, class Sched>
; __device__ __forceinline__ void gemm_phase(LAS unsigned char* lds, const Gemm g, const Sched& S, const Epi& E, int wave_id) {
;     ...
;     for (int i = 0; i < 2; ++i) { int R, C; stage_rc(tid * 16 + i * 8192, R, C); const int Rb = (R & ~31) + perm32(R & 31);
;         voffA[i] = (unsigned)(R * g.lda + C) * 2u; voffB[i] = (unsigned)(Rb * g.ldb + C) * 2u; }
;     const size_t kstep = (size_t)(BK * 2);
;     const size_t hstepA = (size_t)HALF * g.lda * 2, hstepB = (size_t)HALF * g.ldb * 2;
;     const size_t tstepA = 2 * hstepA, tstepB = 2 * hstepB;
;     const unsigned ldsw = (unsigned)wid * 1024u;
;     const int aoff = lds_byte(wr * 64 + fr, fq * 8), boff = lds_byte(wc * 32 + fr, fq * 8);
;     ...
;     Unit cur, nxt; int ui = 0;
;     if (!S.next(0, cur)) return;
;     f32x4 acc[2][2][4][2];
; #pragma unroll
;     for (int a = 0; a < 2; ++a)
; #pragma unroll
;         for (int b = 0; b < 2; ++b)
; #pragma unroll
;             for (int m = 0; m < 4; ++m)
; #pragma unroll
;                 for (int n = 0; n < 2; ++n) acc[a][b][m][n] = (f32x4){0.f, 0.f, 0.f, 0.f};
;     bf16x8 At[4][2], B0[2][2], B1[2][2];
;     const char* cA = (const char*)g.A + (size_t)cur.pm * tstepA; const char* cB = (const char*)g.Bt + (size_t)cur.pn * tstepB;
;     PG8_STAGE(PG8_SB(0, 0), cB, voffB); PG8_STAGE(PG8_SB(0, 1), cB + hstepB, voffB); PG8_STAGE(PG8_SA(0, 0), cA, voffA); PG8_STAGE(PG8_SA(0, 1), cA + hstepA, voffA);
.LBB0_798:
	v_ashrrev_i32_e32 v1, 31, v14
	v_lshrrev_b32_e32 v1, 26, v1
	v_add_u32_e32 v1, v14, v1
	v_ashrrev_i32_e32 v8, 6, v1
	v_bfe_i32 v1, v14, 27, 1
	v_lshlrev_b32_e32 v0, 4, v14
	v_lshrrev_b32_e32 v1, 22, v1
	v_add_u32_e32 v1, v0, v1
	v_and_b32_e32 v1, 0xfffffc00, v1
	v_sub_u32_e32 v1, v0, v1
	v_lshrrev_b32_e32 v2, 4, v1
	v_bitop3_b32 v1, v2, v1, 32 bitop3:0x6c
	v_ashrrev_i32_e32 v3, 31, v1
	v_lshrrev_b32_e32 v3, 26, v3
	v_add_u32_e32 v3, v1, v3
	v_lshlrev_b32_e32 v2, 3, v8
	v_ashrrev_i32_e32 v9, 6, v3
	v_and_b32_e32 v3, 0xc0, v3
	v_and_b32_e32 v2, -16, v2
	v_sub_u32_e32 v1, v1, v3
	v_mov_b32_e32 v3, 1
	v_add_u32_e32 v2, v9, v2
	v_ashrrev_i16_sdwa v1, v3, sext(v1) dst_sel:DWORD dst_unused:UNUSED_PAD src0_sel:DWORD src1_sel:BYTE_0
	v_lshlrev_b32_e32 v4, 5, v8
	v_bfe_i32 v10, v1, 0, 16
	v_lshlrev_b32_e32 v1, 1, v2
	v_lshrrev_b32_e32 v5, 2, v2
	v_and_b32_e32 v6, 3, v9
	s_mov_b32 s7, 0x1fffe0
	v_and_b32_e32 v4, 32, v4
	v_and_b32_e32 v1, 24, v1
	v_and_b32_e32 v5, 4, v5
	v_and_or_b32 v6, v2, s7, v6
	v_or3_b32 v1, v6, v5, v1
	v_add_lshl_u32 v4, v4, v10, 1
	v_add_u32_e32 v0, 0x2000, v0
	v_lshl_add_u32 v130, v1, 11, v4
	v_ashrrev_i32_e32 v1, 31, v0
	v_lshrrev_b32_e32 v1, 22, v1
	v_add_u32_e32 v1, v0, v1
	v_ashrrev_i32_e32 v11, 10, v1
	v_mul_i32_i24_e32 v1, 0x400, v11
	v_sub_u32_e32 v0, v0, v1
	v_lshrrev_b32_e32 v1, 4, v0
	v_bitop3_b32 v0, v1, v0, 32 bitop3:0x6c
	v_lshl_add_u32 v128, v2, 11, v4
	v_ashrrev_i32_e32 v2, 31, v0
	v_lshrrev_b32_e32 v2, 26, v2
	s_add_u32 s2, s92, 0x3400000
	v_add_u32_e32 v2, v0, v2
	s_addc_u32 s21, s93, 0
	v_lshlrev_b32_e32 v1, 3, v11
	v_ashrrev_i32_e32 v12, 6, v2
	v_and_b32_e32 v2, 0xc0, v2
	s_add_u32 s33, s92, 0xa00000
	v_and_b32_e32 v1, -16, v1
	v_sub_u32_e32 v0, v0, v2
	s_addc_u32 s38, s93, 0
	v_add_u32_e32 v1, v12, v1
	v_ashrrev_i16_sdwa v0, v3, sext(v0) dst_sel:DWORD dst_unused:UNUSED_PAD src0_sel:DWORD src1_sel:BYTE_0
	v_and_b32_e32 v3, 3, v12
	s_add_i32 s6, s9, s6
	v_and_or_b32 v3, v1, s7, v3
	s_ashr_i32 s7, s6, 31
	s_lshr_b32 s7, s7, 26
	s_add_i32 s7, s6, s7
	s_ashr_i32 s9, s7, 6
	s_lshl_b32 s9, s9, 3
	s_sub_i32 s10, 0x80, s9
	v_bfe_i32 v13, v0, 0, 16
	v_lshlrev_b32_e32 v0, 1, v1
	v_lshrrev_b32_e32 v2, 2, v1
	s_min_i32 s10, s10, 8
	v_and_b32_e32 v0, 24, v0
	v_and_b32_e32 v2, 4, v2
	s_abs_i32 s11, s10
	v_or3_b32 v0, v3, v2, v0
	v_cvt_f32_u32_e32 v3, s11
	v_lshlrev_b32_e32 v4, 5, v11
	v_and_b32_e32 v4, 32, v4
	v_add_lshl_u32 v2, v4, v13, 1
	v_lshl_add_u32 v134, v0, 11, v2
	v_rcp_iflag_f32_e32 v0, v3
	s_sub_i32 s13, 0, s11
	s_andn2_b32 s7, s7, 63
	s_sub_i32 s6, s6, s7
	v_mul_f32_e32 v0, 0x4f7ffffe, v0
	v_cvt_u32_f32_e32 v0, v0
	s_abs_i32 s12, s6
	s_xor_b32 s7, s6, s10
	s_lshr_b32 s8, s80, 8
	v_readfirstlane_b32 s14, v0
	s_mul_i32 s13, s13, s14
	s_mul_hi_u32 s13, s14, s13
	s_add_i32 s14, s14, s13
	s_mul_hi_u32 s13, s12, s14
	s_mul_i32 s14, s13, s11
	s_sub_i32 s12, s12, s14
	s_lshl_b32 s39, s97, 10
	s_ashr_i32 s7, s7, 31
	s_add_i32 s14, s13, 1
	s_sub_i32 s15, s12, s11
	s_cmp_ge_u32 s12, s11
	s_cselect_b32 s13, s14, s13
	s_cselect_b32 s12, s15, s12
	s_add_i32 s14, s13, 1
	s_cmp_ge_u32 s12, s11
	s_cselect_b32 s11, s14, s13
	s_xor_b32 s11, s11, s7
	s_sub_i32 s26, s11, s7
	s_mul_i32 s7, s26, s10
	s_sub_i32 s6, s6, s7
	s_add_i32 s28, s9, s6
	s_and_b32 s7, s28, 7
	s_andn2_b32 s28, s28, 7
	s_add_i32 s28, s28, s26
	s_mov_b32 s26, s7
	s_ashr_i32 s29, s28, 31
	s_ashr_i32 s27, s26, 31
	s_lshl_b64 s[6:7], s[28:29], 19
	s_lshl_b64 s[10:11], s[26:27], 19
	s_add_u32 s34, s33, s10
	s_addc_u32 s35, s38, s11
	s_add_i32 s27, s39, 0
	s_add_i32 m0, s27, 0x10000
	v_lshl_add_u32 v132, v1, 11, v2
	global_load_lds_dwordx4 v130, s[34:35]
	s_add_i32 m0, s27, 0x12000
	s_add_u32 s10, s34, 0x40000
	global_load_lds_dwordx4 v134, s[34:35]
	s_addc_u32 s11, s35, 0
	s_add_i32 m0, s27, 0x14000
	v_mov_b32_e32 v131, 0
	global_load_lds_dwordx4 v130, s[10:11]
	s_add_i32 m0, s27, 0x16000
	s_add_u32 s30, s2, s6
	s_addc_u32 s31, s21, s7
	s_add_i32 s29, s27, 0x2000
	global_load_lds_dwordx4 v134, s[10:11]
	s_mov_b32 m0, s27
	s_add_u32 s6, s30, 0x40000
	global_load_lds_dwordx4 v128, s[30:31]
	s_mov_b32 m0, s29
	s_addc_u32 s7, s31, 0
	s_add_i32 s44, s27, 0x4000
	global_load_lds_dwordx4 v132, s[30:31]
	s_mov_b32 m0, s44
	s_add_i32 s45, s27, 0x6000
	global_load_lds_dwordx4 v128, s[6:7]
	s_mov_b32 m0, s45
	v_mov_b32_e32 v135, v131
	global_load_lds_dwordx4 v132, s[6:7]
	v_mov_b32_e32 v129, v131
	v_mov_b32_e32 v133, v131
	s_cmp_eq_u32 s8, 1
	v_lshl_add_u64 v[6:7], s[34:35], 0, v[130:131]
	v_lshl_add_u64 v[4:5], s[34:35], 0, v[134:135]
	v_lshl_add_u64 v[0:1], s[30:31], 0, v[128:129]
	s_cselect_b64 s[6:7], -1, 0
	s_cmp_lg_u32 s8, 1
	v_lshl_add_u64 v[2:3], s[30:31], 0, v[132:133]
	s_cbranch_scc1 .LBB0_800
	s_barrier
;     __device__ bool next(int i, Unit& u) const { if (r0 + i >= r1) return false; return base.next(r0 + i, u); }
;     __device__ bool next(int i, Unit& u) const { const int L = i * G + c; if (L >= 256) return false; u.pm = L; u.pn = L >> 3; return true; }
; #define PG8_STAGE(bufoff, gbase, voff) do { _Pragma("unroll") for (int _i = 0; _i < 2; ++_i) \
;         __builtin_amdgcn_global_load_lds((const unsigned*)((const char*)(gbase) + (voff)[_i]), (LAS unsigned*)(lds + (bufoff) + ldsw + _i * 8192), 16, 0, 0); } while (0)
; #define PG8_WAIT_V(n) asm volatile("s_waitcnt vmcnt(" #n ")" ::: "memory")
; #define PG8_BAR __builtin_amdgcn_s_barrier()
;     __device__ bool next(int i, Unit& u) const {
;         const long L = (long)i * G + c; if (L >= nwg) return false;
;         int wgid = (int)L; { const int q = nwg / NXCD, r = nwg % NXCD, xcd = wgid % NXCD, off = wgid / NXCD; wgid = (xcd < r ? xcd * (q + 1) : r * (q + 1) + (xcd - r) * q) + off; }
;         const int nig = WGM * nN, gid = wgid / nig, fm = gid * WGM, gsz = (nM - fm) < WGM ? (nM - fm) : WGM;
;         u.pm = fm + ((wgid % nig) % gsz); u.pn = (wgid % nig) / gsz; return true;
; template <class Epi, class Sched>
; __device__ __forceinline__ void gemm_phase(LAS unsigned char* lds, const Gemm g, const Sched& S, const Epi& E, int wave_id) {
;     ...
;     PG8_STAGE(PG8_SB(0, 0), cB, voffB); PG8_STAGE(PG8_SB(0, 1), cB + hstepB, voffB); PG8_STAGE(PG8_SA(0, 0), cA, voffA); PG8_STAGE(PG8_SA(0, 1), cA + hstepA, voffA);
;     if (wr == 1) PG8_BAR;
;     PG8_WAIT_V(2); PG8_BAR;
;     PG8_STAGE(PG8_SB(1, 0), cB + kstep, voffB); PG8_STAGE(PG8_SA(1, 0), cA + kstep, voffA); PG8_STAGE(PG8_SB(1, 1), cB + hstepB + kstep, voffB);
;     PG8_WAIT_V(6); PG8_BAR;
;     for (;;) {
;         const bool has_next = S.next(ui + 1, nxt);
;         const char* nA = has_next ? (const char*)g.A + (size_t)nxt.pm * tstepA : cA; const char* nB = has_next ? (const char*)g.Bt + (size_t)nxt.pn * tstepB : cB;
.LBB0_800:
	v_lshrrev_b32_e32 v16, 1, v14
	v_and_b32_e32 v16, 24, v16
	v_and_b32_e32 v15, 15, v14
	v_lshlrev_b32_e32 v17, 1, v16
	v_lshlrev_b32_e32 v14, 2, v14
	v_lshl_or_b32 v156, s8, 6, v15
	v_lshl_or_b32 v15, v15, 6, v17
	s_lshl_b32 s8, s8, 13
	v_and_b32_e32 v14, 32, v14
	v_bitop3_b32 v17, v15, s8, v14 bitop3:0xde
	s_lshl_b32 s8, s97, 5
	s_and_b32 s16, s8, 0x60
	s_lshl_b32 s8, s16, 7
	v_bitop3_b32 v157, v15, s8, v14 bitop3:0xde
	s_mov_b64 s[8:9], 0x80
	s_add_i32 m0, s27, 0x18000
	v_lshl_add_u64 v[6:7], v[6:7], 0, s[8:9]
	s_waitcnt vmcnt(2)
	s_barrier
	global_load_lds_dwordx4 v[6:7], off
	v_lshl_add_u64 v[4:5], v[4:5], 0, s[8:9]
	s_add_i32 m0, s27, 0x1a000
	s_add_i32 s46, s27, 0x8000
	s_add_i32 s47, s27, 0xa000
	global_load_lds_dwordx4 v[4:5], off
	v_lshl_add_u64 v[0:1], v[0:1], 0, s[8:9]
	s_mov_b32 m0, s46
	s_add_u32 s10, s34, 0x40080
	global_load_lds_dwordx4 v[0:1], off
	v_lshl_add_u64 v[0:1], v[2:3], 0, s[8:9]
	s_mov_b32 m0, s47
	s_addc_u32 s11, s35, 0
	global_load_lds_dwordx4 v[0:1], off
	s_add_i32 m0, s27, 0x1c000
	s_nop 0
	global_load_lds_dwordx4 v130, s[10:11]
	s_add_i32 m0, s27, 0x1e000
	s_cmpk_lt_u32 s80, 0x100
	global_load_lds_dwordx4 v134, s[10:11]
	s_cselect_b64 s[10:11], -1, 0
	s_add_u32 s12, s92, 0x1f400000
	s_addc_u32 s13, s93, 0
	s_add_u32 s14, s92, 0xb400000
	s_addc_u32 s15, s93, 0
	s_mul_hi_i32 s17, s4, 3
	s_mul_i32 s4, s4, 3
	s_add_u32 s4, s4, s66
	s_addc_u32 s5, s17, s5
	s_ashr_i32 s17, s4, 31
	s_lshr_b32 s17, s17, 29
	s_add_i32 s17, s4, s17
	s_ashr_i32 s18, s17, 3
	s_and_b32 s17, s17, -8
	s_sub_i32 s17, s4, s17
	s_lshl_b32 s19, s17, 7
	s_cmp_lt_i32 s17, 0
	s_mulk_i32 s17, 0x81
	s_cselect_b32 s17, s17, s19
	s_add_i32 s17, s17, s18
	s_ashr_i32 s18, s17, 31
	s_lshr_b32 s18, s18, 26
	s_add_i32 s18, s17, s18
	s_ashr_i32 s19, s18, 6
	s_lshl_b32 s19, s19, 3
	s_sub_i32 s20, 0x80, s19
	s_min_i32 s20, s20, 8
	s_abs_i32 s22, s20
	v_cvt_f32_u32_e32 v2, s22
	v_mov_b64_e32 v[0:1], 0x400
	v_cmp_lt_i64_e64 s[36:37], s[4:5], v[0:1]
	s_andn2_b32 s18, s18, 63
	v_rcp_iflag_f32_e32 v0, v2
	s_sub_i32 s4, s17, s18
	s_sub_i32 s17, 0, s22
	v_or_b32_e32 v158, s16, v16
	v_mul_f32_e32 v0, 0x4f7ffffe, v0
	v_cvt_u32_f32_e32 v0, v0
	s_abs_i32 s16, s4
	s_xor_b32 s5, s4, s20
	s_ashr_i32 s5, s5, 31
	v_readfirstlane_b32 s18, v0
	s_mul_i32 s17, s17, s18
	s_mul_hi_u32 s17, s18, s17
	s_add_i32 s18, s18, s17
	s_mul_hi_u32 s17, s16, s18
	s_mul_i32 s18, s17, s22
	s_sub_i32 s16, s16, s18
	s_add_i32 s18, s17, 1
	s_sub_i32 s23, s16, s22
	s_cmp_ge_u32 s16, s22
	s_cselect_b32 s17, s18, s17
	v_lshlrev_b32_e32 v0, 14, v8
	s_cselect_b32 s16, s23, s16
	s_add_i32 s18, s17, 1
	v_and_b32_e32 v0, 0xffff8000, v0
	s_cmp_ge_u32 s16, s22
	v_lshl_add_u32 v0, v9, 11, v0
	v_and_b32_e32 v1, 1, v8
	s_cselect_b32 s16, s18, s17
	v_lshl_or_b32 v0, v1, 6, v0
	s_xor_b32 s16, s16, s5
	v_lshl_add_u32 v136, v10, 1, v0
	v_lshlrev_b32_e32 v0, 14, v11
	s_sub_i32 s16, s16, s5
	v_and_b32_e32 v0, 0xffff8000, v0
	s_waitcnt vmcnt(6)
	s_mul_i32 s5, s16, s20
	v_lshl_add_u32 v0, v12, 11, v0
	v_and_b32_e32 v1, 1, v11
	s_sub_i32 s4, s4, s5
	v_lshl_or_b32 v0, v1, 6, v0
	s_add_i32 s48, 0, 0x10000
	s_add_i32 s49, 0, 0x14000
	s_add_i32 s18, s19, s4
	s_and_b32 s5, s18, 7
	s_andn2_b32 s18, s18, 7
	s_add_i32 s18, s18, s16
	s_mov_b32 s16, s5
	v_mov_b32_e32 v137, v131
	v_lshl_add_u32 v138, v13, 1, v0
	v_mov_b32_e32 v139, v131
	v_add_u32_e32 v159, s48, v157
	v_add_u32_e32 v160, s49, v157
	v_add_u32_e32 v161, 0, v17
	s_mov_b32 s20, 0x437f0000
	s_mov_b32 s50, 0xb400000
	s_barrier
	s_branch .LBB0_803

;     __device__ bool next(int i, Unit& u) const { if (r0 + i >= r1) return false; return base.next(r0 + i, u); }
;     __device__ bool next(int i, Unit& u) const { const int L = i * G + c; if (L >= 256) return false; u.pm = L; u.pn = L >> 3; return true; }
;     __device__ bool next(int i, Unit& u) const {
;         const long L = (long)i * G + c; if (L >= nwg) return false;
;         int wgid = (int)L; { const int q = nwg / NXCD, r = nwg % NXCD, xcd = wgid % NXCD, off = wgid / NXCD; wgid = (xcd < r ? xcd * (q + 1) : r * (q + 1) + (xcd - r) * q) + off; }
;         const int nig = WGM * nN, gid = wgid / nig, fm = gid * WGM, gsz = (nM - fm) < WGM ? (nM - fm) : WGM;
;         u.pm = fm + ((wgid % nig) % gsz); u.pn = (wgid % nig) / gsz; return true;
; template <class Epi, class Sched>
; __device__ __forceinline__ void gemm_phase(LAS unsigned char* lds, const Gemm g, const Sched& S, const Epi& E, int wave_id) {
;     ...
;     for (int i = 0; i < 2; ++i) { int R, C; stage_rc(tid * 16 + i * 8192, R, C); const int Rb = (R & ~31) + perm32(R & 31);
;         voffA[i] = (unsigned)(R * g.lda + C) * 2u; voffB[i] = (unsigned)(Rb * g.ldb + C) * 2u; }
;     const size_t kstep = (size_t)(BK * 2);
;     const size_t hstepA = (size_t)HALF * g.lda * 2, hstepB = (size_t)HALF * g.ldb * 2;
;     const size_t tstepA = 2 * hstepA, tstepB = 2 * hstepB;
;     const unsigned ldsw = (unsigned)wid * 1024u;
;     const int aoff = lds_byte(wr * 64 + fr, fq * 8), boff = lds_byte(wc * 32 + fr, fq * 8);
;     ...
;     Unit cur, nxt; int ui = 0;
;     if (!S.next(0, cur)) return;
;     f32x4 acc[2][2][4][2];
; #pragma unroll
;     for (int a = 0; a < 2; ++a)
; #pragma unroll
;         for (int b = 0; b < 2; ++b)
; #pragma unroll
;             for (int m = 0; m < 4; ++m)
; #pragma unroll
;                 for (int n = 0; n < 2; ++n) acc[a][b][m][n] = (f32x4){0.f, 0.f, 0.f, 0.f};
;     bf16x8 At[4][2], B0[2][2], B1[2][2];
;     const char* cA = (const char*)g.A + (size_t)cur.pm * tstepA; const char* cB = (const char*)g.Bt + (size_t)cur.pn * tstepB;
;     PG8_STAGE(PG8_SB(0, 0), cB, voffB); PG8_STAGE(PG8_SB(0, 1), cB + hstepB, voffB); PG8_STAGE(PG8_SA(0, 0), cA, voffA); PG8_STAGE(PG8_SA(0, 1), cA + hstepA, voffA);
.LBB0_857:
	v_ashrrev_i32_e32 v1, 31, v14
	v_lshrrev_b32_e32 v1, 26, v1
	v_add_u32_e32 v1, v14, v1
	v_ashrrev_i32_e32 v8, 6, v1
	v_bfe_i32 v1, v14, 27, 1
	v_lshlrev_b32_e32 v0, 4, v14
	v_lshrrev_b32_e32 v1, 22, v1
	v_add_u32_e32 v1, v0, v1
	v_and_b32_e32 v1, 0xfffffc00, v1
	v_sub_u32_e32 v1, v0, v1
	v_lshrrev_b32_e32 v2, 4, v1
	v_bitop3_b32 v1, v2, v1, 32 bitop3:0x6c
	v_ashrrev_i32_e32 v3, 31, v1
	v_lshrrev_b32_e32 v3, 26, v3
	v_add_u32_e32 v3, v1, v3
	v_lshlrev_b32_e32 v2, 3, v8
	v_ashrrev_i32_e32 v9, 6, v3
	v_and_b32_e32 v3, 0xc0, v3
	v_and_b32_e32 v2, -16, v2
	v_sub_u32_e32 v1, v1, v3
	v_mov_b32_e32 v3, 1
	v_add_u32_e32 v2, v9, v2
	v_ashrrev_i16_sdwa v1, v3, sext(v1) dst_sel:DWORD dst_unused:UNUSED_PAD src0_sel:DWORD src1_sel:BYTE_0
	v_lshlrev_b32_e32 v4, 5, v8
	v_bfe_i32 v10, v1, 0, 16
	v_lshlrev_b32_e32 v1, 1, v2
	v_lshrrev_b32_e32 v5, 2, v2
	v_and_b32_e32 v6, 3, v9
	s_mov_b32 s7, 0x1fffe0
	v_and_b32_e32 v4, 32, v4
	v_and_b32_e32 v1, 24, v1
	v_and_b32_e32 v5, 4, v5
	v_and_or_b32 v6, v2, s7, v6
	v_or3_b32 v1, v6, v5, v1
	v_add_lshl_u32 v4, v4, v10, 1
	v_add_u32_e32 v0, 0x2000, v0
	v_lshl_add_u32 v130, v1, 11, v4
	v_ashrrev_i32_e32 v1, 31, v0
	v_lshrrev_b32_e32 v1, 22, v1
	v_add_u32_e32 v1, v0, v1
	v_ashrrev_i32_e32 v11, 10, v1
	v_mul_i32_i24_e32 v1, 0x400, v11
	v_sub_u32_e32 v0, v0, v1
	v_lshrrev_b32_e32 v1, 4, v0
	v_bitop3_b32 v0, v1, v0, 32 bitop3:0x6c
	v_lshl_add_u32 v128, v2, 11, v4
	v_ashrrev_i32_e32 v2, 31, v0
	v_lshrrev_b32_e32 v2, 26, v2
	s_add_u32 s2, s92, 0x3400000
	v_add_u32_e32 v2, v0, v2
	s_addc_u32 s3, s93, 0
	v_lshlrev_b32_e32 v1, 3, v11
	v_ashrrev_i32_e32 v12, 6, v2
	v_and_b32_e32 v2, 0xc0, v2
	s_add_u32 s21, s92, 0xa00000
	v_and_b32_e32 v1, -16, v1
	v_sub_u32_e32 v0, v0, v2
	s_addc_u32 s33, s93, 0
	v_add_u32_e32 v1, v12, v1
	v_ashrrev_i16_sdwa v0, v3, sext(v0) dst_sel:DWORD dst_unused:UNUSED_PAD src0_sel:DWORD src1_sel:BYTE_0
	v_and_b32_e32 v3, 3, v12
	s_add_i32 s6, s9, s6
	v_and_or_b32 v3, v1, s7, v3
	s_ashr_i32 s7, s6, 31
	s_lshr_b32 s7, s7, 26
	s_add_i32 s7, s6, s7
	s_ashr_i32 s9, s7, 6
	s_lshl_b32 s9, s9, 3
	s_sub_i32 s10, 0x80, s9
	v_bfe_i32 v13, v0, 0, 16
	v_lshlrev_b32_e32 v0, 1, v1
	v_lshrrev_b32_e32 v2, 2, v1
	s_min_i32 s10, s10, 8
	v_and_b32_e32 v0, 24, v0
	v_and_b32_e32 v2, 4, v2
	s_abs_i32 s11, s10
	v_or3_b32 v0, v3, v2, v0
	v_cvt_f32_u32_e32 v3, s11
	v_lshlrev_b32_e32 v4, 5, v11
	v_and_b32_e32 v4, 32, v4
	v_add_lshl_u32 v2, v4, v13, 1
	v_lshl_add_u32 v134, v0, 11, v2
	v_rcp_iflag_f32_e32 v0, v3
	s_sub_i32 s13, 0, s11
	s_andn2_b32 s7, s7, 63
	s_sub_i32 s6, s6, s7
	v_mul_f32_e32 v0, 0x4f7ffffe, v0
	v_cvt_u32_f32_e32 v0, v0
	s_abs_i32 s12, s6
	s_xor_b32 s7, s6, s10
	s_lshr_b32 s8, s80, 8
	v_readfirstlane_b32 s14, v0
	s_mul_i32 s13, s13, s14
	s_mul_hi_u32 s13, s14, s13
	s_add_i32 s14, s14, s13
	s_mul_hi_u32 s13, s12, s14
	s_mul_i32 s14, s13, s11
	s_sub_i32 s12, s12, s14
	s_lshl_b32 s38, s97, 10
	s_ashr_i32 s7, s7, 31
	s_add_i32 s14, s13, 1
	s_sub_i32 s15, s12, s11
	s_cmp_ge_u32 s12, s11
	s_cselect_b32 s13, s14, s13
	s_cselect_b32 s12, s15, s12
	s_add_i32 s14, s13, 1
	s_cmp_ge_u32 s12, s11
	s_cselect_b32 s11, s14, s13
	s_xor_b32 s11, s11, s7
	s_sub_i32 s26, s11, s7
	s_mul_i32 s7, s26, s10
	s_sub_i32 s6, s6, s7
	s_add_i32 s28, s9, s6
	s_and_b32 s7, s28, 7
	s_andn2_b32 s28, s28, 7
	s_add_i32 s28, s28, s26
	s_mov_b32 s26, s7
	s_ashr_i32 s29, s28, 31
	s_ashr_i32 s27, s26, 31
	s_lshl_b64 s[6:7], s[28:29], 19
	s_lshl_b64 s[10:11], s[26:27], 19
	s_add_u32 s34, s21, s10
	s_addc_u32 s35, s33, s11
	s_add_i32 s27, s38, 0
	s_add_i32 m0, s27, 0x10000
	v_lshl_add_u32 v132, v1, 11, v2
	global_load_lds_dwordx4 v130, s[34:35]
	s_add_i32 m0, s27, 0x12000
	s_add_u32 s10, s34, 0x40000
	global_load_lds_dwordx4 v134, s[34:35]
	s_addc_u32 s11, s35, 0
	s_add_i32 m0, s27, 0x14000
	v_mov_b32_e32 v131, 0
	global_load_lds_dwordx4 v130, s[10:11]
	s_add_i32 m0, s27, 0x16000
	s_add_u32 s30, s2, s6
	s_addc_u32 s31, s3, s7
	s_add_i32 s29, s27, 0x2000
	global_load_lds_dwordx4 v134, s[10:11]
	s_mov_b32 m0, s27
	s_add_u32 s6, s30, 0x40000
	global_load_lds_dwordx4 v128, s[30:31]
	s_mov_b32 m0, s29
	s_addc_u32 s7, s31, 0
	s_add_i32 s39, s27, 0x4000
	global_load_lds_dwordx4 v132, s[30:31]
	s_mov_b32 m0, s39
	s_add_i32 s40, s27, 0x6000
	global_load_lds_dwordx4 v128, s[6:7]
	s_mov_b32 m0, s40
	v_mov_b32_e32 v135, v131
	global_load_lds_dwordx4 v132, s[6:7]
	v_mov_b32_e32 v129, v131
	v_mov_b32_e32 v133, v131
	s_cmp_eq_u32 s8, 1
	v_lshl_add_u64 v[6:7], s[34:35], 0, v[130:131]
	v_lshl_add_u64 v[4:5], s[34:35], 0, v[134:135]
	v_lshl_add_u64 v[0:1], s[30:31], 0, v[128:129]
	s_cselect_b64 s[6:7], -1, 0
	s_cmp_lg_u32 s8, 1
	v_lshl_add_u64 v[2:3], s[30:31], 0, v[132:133]
	s_cbranch_scc1 .LBB0_859
	s_barrier
;     __device__ bool next(int i, Unit& u) const { if (r0 + i >= r1) return false; return base.next(r0 + i, u); }
;     __device__ bool next(int i, Unit& u) const { const int L = i * G + c; if (L >= 256) return false; u.pm = L; u.pn = L >> 3; return true; }
; #define PG8_STAGE(bufoff, gbase, voff) do { _Pragma("unroll") for (int _i = 0; _i < 2; ++_i) \
;         __builtin_amdgcn_global_load_lds((const unsigned*)((const char*)(gbase) + (voff)[_i]), (LAS unsigned*)(lds + (bufoff) + ldsw + _i * 8192), 16, 0, 0); } while (0)
; #define PG8_WAIT_V(n) asm volatile("s_waitcnt vmcnt(" #n ")" ::: "memory")
; #define PG8_BAR __builtin_amdgcn_s_barrier()
;     __device__ bool next(int i, Unit& u) const {
;         const long L = (long)i * G + c; if (L >= nwg) return false;
;         int wgid = (int)L; { const int q = nwg / NXCD, r = nwg % NXCD, xcd = wgid % NXCD, off = wgid / NXCD; wgid = (xcd < r ? xcd * (q + 1) : r * (q + 1) + (xcd - r) * q) + off; }
;         const int nig = WGM * nN, gid = wgid / nig, fm = gid * WGM, gsz = (nM - fm) < WGM ? (nM - fm) : WGM;
;         u.pm = fm + ((wgid % nig) % gsz); u.pn = (wgid % nig) / gsz; return true;
; template <class Epi, class Sched>
; __device__ __forceinline__ void gemm_phase(LAS unsigned char* lds, const Gemm g, const Sched& S, const Epi& E, int wave_id) {
;     ...
;     PG8_STAGE(PG8_SB(0, 0), cB, voffB); PG8_STAGE(PG8_SB(0, 1), cB + hstepB, voffB); PG8_STAGE(PG8_SA(0, 0), cA, voffA); PG8_STAGE(PG8_SA(0, 1), cA + hstepA, voffA);
;     if (wr == 1) PG8_BAR;
;     PG8_WAIT_V(2); PG8_BAR;
;     PG8_STAGE(PG8_SB(1, 0), cB + kstep, voffB); PG8_STAGE(PG8_SA(1, 0), cA + kstep, voffA); PG8_STAGE(PG8_SB(1, 1), cB + hstepB + kstep, voffB);
;     PG8_WAIT_V(6); PG8_BAR;
;     for (;;) {
;         const bool has_next = S.next(ui + 1, nxt);
;         const char* nA = has_next ? (const char*)g.A + (size_t)nxt.pm * tstepA : cA; const char* nB = has_next ? (const char*)g.Bt + (size_t)nxt.pn * tstepB : cB;
.LBB0_859:
	v_lshrrev_b32_e32 v16, 1, v14
	v_and_b32_e32 v16, 24, v16
	v_and_b32_e32 v15, 15, v14
	v_lshlrev_b32_e32 v17, 1, v16
	v_lshlrev_b32_e32 v14, 2, v14
	v_lshl_or_b32 v156, s8, 6, v15
	v_lshl_or_b32 v15, v15, 6, v17
	s_lshl_b32 s8, s8, 13
	v_and_b32_e32 v14, 32, v14
	v_bitop3_b32 v17, v15, s8, v14 bitop3:0xde
	s_lshl_b32 s8, s97, 5
	s_and_b32 s16, s8, 0x60
	s_lshl_b32 s8, s16, 7
	v_bitop3_b32 v157, v15, s8, v14 bitop3:0xde
	s_mov_b64 s[8:9], 0x80
	s_add_i32 m0, s27, 0x18000
	v_lshl_add_u64 v[6:7], v[6:7], 0, s[8:9]
	s_waitcnt vmcnt(2)
	s_barrier
	global_load_lds_dwordx4 v[6:7], off
	v_lshl_add_u64 v[4:5], v[4:5], 0, s[8:9]
	s_add_i32 m0, s27, 0x1a000
	s_add_i32 s41, s27, 0x8000
	s_add_i32 s42, s27, 0xa000
	global_load_lds_dwordx4 v[4:5], off
	v_lshl_add_u64 v[0:1], v[0:1], 0, s[8:9]
	s_mov_b32 m0, s41
	s_add_u32 s10, s34, 0x40080
	global_load_lds_dwordx4 v[0:1], off
	v_lshl_add_u64 v[0:1], v[2:3], 0, s[8:9]
	s_mov_b32 m0, s42
	s_addc_u32 s11, s35, 0
	global_load_lds_dwordx4 v[0:1], off
	s_add_i32 m0, s27, 0x1c000
	s_nop 0
	global_load_lds_dwordx4 v130, s[10:11]
	s_add_i32 m0, s27, 0x1e000
	s_cmpk_lt_u32 s80, 0x100
	global_load_lds_dwordx4 v134, s[10:11]
	s_cselect_b64 s[10:11], -1, 0
	s_add_u32 s12, s92, 0x1f400000
	s_addc_u32 s13, s93, 0
	s_add_u32 s14, s92, 0xb400000
	s_addc_u32 s15, s93, 0
	s_mul_hi_i32 s17, s4, 3
	s_mul_i32 s4, s4, 3
	s_add_u32 s4, s4, s66
	s_addc_u32 s5, s17, s5
	s_ashr_i32 s17, s4, 31
	s_lshr_b32 s17, s17, 29
	s_add_i32 s17, s4, s17
	s_ashr_i32 s18, s17, 3
	s_and_b32 s17, s17, -8
	s_sub_i32 s17, s4, s17
	s_lshl_b32 s19, s17, 7
	s_cmp_lt_i32 s17, 0
	s_mulk_i32 s17, 0x81
	s_cselect_b32 s17, s17, s19
	s_add_i32 s17, s17, s18
	s_ashr_i32 s18, s17, 31
	s_lshr_b32 s18, s18, 26
	s_add_i32 s18, s17, s18
	s_ashr_i32 s19, s18, 6
	s_lshl_b32 s19, s19, 3
	s_sub_i32 s20, 0x80, s19
	s_min_i32 s20, s20, 8
	s_abs_i32 s22, s20
	v_cvt_f32_u32_e32 v2, s22
	v_mov_b64_e32 v[0:1], 0x400
	v_cmp_lt_i64_e64 s[36:37], s[4:5], v[0:1]
	s_andn2_b32 s18, s18, 63
	v_rcp_iflag_f32_e32 v0, v2
	s_sub_i32 s4, s17, s18
	s_sub_i32 s17, 0, s22
	v_or_b32_e32 v158, s16, v16
	v_mul_f32_e32 v0, 0x4f7ffffe, v0
	v_cvt_u32_f32_e32 v0, v0
	s_abs_i32 s16, s4
	s_xor_b32 s5, s4, s20
	s_ashr_i32 s5, s5, 31
	v_readfirstlane_b32 s18, v0
	s_mul_i32 s17, s17, s18
	s_mul_hi_u32 s17, s18, s17
	s_add_i32 s18, s18, s17
	s_mul_hi_u32 s17, s16, s18
	s_mul_i32 s18, s17, s22
	s_sub_i32 s16, s16, s18
	s_add_i32 s18, s17, 1
	s_sub_i32 s23, s16, s22
	s_cmp_ge_u32 s16, s22
	s_cselect_b32 s17, s18, s17
	v_lshlrev_b32_e32 v0, 14, v8
	s_cselect_b32 s16, s23, s16
	s_add_i32 s18, s17, 1
	v_and_b32_e32 v0, 0xffff8000, v0
	s_cmp_ge_u32 s16, s22
	v_lshl_add_u32 v0, v9, 11, v0
	v_and_b32_e32 v1, 1, v8
	s_cselect_b32 s16, s18, s17
	v_lshl_or_b32 v0, v1, 6, v0
	s_xor_b32 s16, s16, s5
	v_lshl_add_u32 v136, v10, 1, v0
	v_lshlrev_b32_e32 v0, 14, v11
	s_sub_i32 s16, s16, s5
	v_and_b32_e32 v0, 0xffff8000, v0
	s_waitcnt vmcnt(6)
	s_mul_i32 s5, s16, s20
	v_lshl_add_u32 v0, v12, 11, v0
	v_and_b32_e32 v1, 1, v11
	s_sub_i32 s4, s4, s5
	v_lshl_or_b32 v0, v1, 6, v0
	s_add_i32 s43, 0, 0x10000
	s_add_i32 s44, 0, 0x14000
	s_add_i32 s18, s19, s4
	s_and_b32 s5, s18, 7
	s_andn2_b32 s18, s18, 7
	s_add_i32 s18, s18, s16
	s_mov_b32 s16, s5
	v_mov_b32_e32 v137, v131
	v_lshl_add_u32 v138, v13, 1, v0
	v_mov_b32_e32 v139, v131
	v_add_u32_e32 v159, s43, v157
	v_add_u32_e32 v160, s44, v157
	v_add_u32_e32 v161, 0, v17
	s_mov_b32 s20, 0x437f0000
	s_mov_b32 s45, 0xb400000
	s_barrier
	s_branch .LBB0_862
